# speedup vs baseline: 1.0088x; 1.0049x over previous
; __device__ __forceinline__ u16 f2bf(float f) { return (u16)(pack2(f, 0.f) & 0xffffu); }
; __device__ void ga_items(const Ctx& p) {
;     ...
;   for (int item = blockIdx.x; item < NTOK / 64; item += gridDim.x) {
;     const long row0 = (long)item * 64 + (w >> 1) * 16;
;     const u16* ap = xb + (row0 + fr) * DM + (w & 1) * 2048 + fq * 8;
;     const u16* bp = wt + (long)fr * DM + (w & 1) * 2048 + fq * 8;
;     f32x4 acc = {0.f, 0.f, 0.f, 0.f};
; #pragma unroll 1
;     for (int k0 = 0; k0 < 64; k0 += 8) {
;       bf16x8 fa[8], fb[8];
; #pragma unroll
;       for (int u = 0; u < 8; ++u) { fa[u] = *(const bf16x8*)(ap + (k0 + u) * 32); fb[u] = *(const bf16x8*)(bp + (k0 + u) * 32); }
; #pragma unroll
;       for (int u = 0; u < 8; ++u) acc = __builtin_amdgcn_mfma_f32_16x16x32_bf16(fa[u], fb[u], acc, 0, 0, 0);
;     }
;     __syncthreads();
;     *(f32x4*)(red + (w * 64 + lane) * 4) = acc;
;     __syncthreads();
;     if ((w & 1) == 0) {
;       const f32x4 o = *(const f32x4*)(red + ((w + 1) * 64 + lane) * 4);
; #pragma unroll
;       for (int r = 0; r < 4; ++r) h0[(row0 + fq * 4 + r) * H0LD + C_GA + fr] = f2bf(acc[r] + o[r]);
;     }
;   }
.LBB0_379:
	v_lshl_add_u64 v[60:61], v[26:27], 0, v[0:1]
	v_add_co_u32_e32 v64, vcc, 0xf800000, v60
	v_lshl_add_u64 v[56:57], v[24:25], 0, v[0:1]
	s_nop 0
	v_addc_co_u32_e32 v65, vcc, 0, v61, vcc
	global_load_dwordx4 v[28:31], v[56:57], off
	global_load_dwordx4 v[32:35], v[56:57], off offset:64
	global_load_dwordx4 v[36:39], v[56:57], off offset:128
	global_load_dwordx4 v[40:43], v[56:57], off offset:192
	global_load_dwordx4 v[44:47], v[56:57], off offset:256
	global_load_dwordx4 v[48:51], v[56:57], off offset:320
	global_load_dwordx4 v[52:55], v[56:57], off offset:384
	global_load_dwordx4 v[100:103], v[56:57], off offset:448
	global_load_dwordx4 v[68:71], v[64:65], off
	global_load_dwordx4 v[72:75], v[64:65], off offset:64
	global_load_dwordx4 v[76:79], v[64:65], off offset:128
	global_load_dwordx4 v[80:83], v[64:65], off offset:192
	global_load_dwordx4 v[84:87], v[64:65], off offset:256
	global_load_dwordx4 v[88:91], v[64:65], off offset:320
	global_load_dwordx4 v[92:95], v[64:65], off offset:384
	global_load_dwordx4 v[96:99], v[64:65], off offset:448
	s_add_i32 s5, s5, 8
	v_lshl_add_u64 v[24:25], v[24:25], 0, s[74:75]
	s_cmp_gt_u32 s5, 55
	v_lshl_add_u64 v[26:27], v[26:27], 0, s[74:75]
	s_waitcnt vmcnt(7)
	v_mfma_f32_16x16x32_bf16 v[2:5], v[28:31], v[68:71], v[2:5]
	s_waitcnt vmcnt(6)
	v_mfma_f32_16x16x32_bf16 v[2:5], v[32:35], v[72:75], v[2:5]
	s_waitcnt vmcnt(5)
	v_mfma_f32_16x16x32_bf16 v[2:5], v[36:39], v[76:79], v[2:5]
	s_waitcnt vmcnt(4)
	v_mfma_f32_16x16x32_bf16 v[2:5], v[40:43], v[80:83], v[2:5]
	s_waitcnt vmcnt(3)
	v_mfma_f32_16x16x32_bf16 v[2:5], v[44:47], v[84:87], v[2:5]
	s_waitcnt vmcnt(2)
	v_mfma_f32_16x16x32_bf16 v[2:5], v[48:51], v[88:91], v[2:5]
	s_waitcnt vmcnt(1)
	v_mfma_f32_16x16x32_bf16 v[2:5], v[52:55], v[92:95], v[2:5]
	s_waitcnt vmcnt(0)
	v_mfma_f32_16x16x32_bf16 v[2:5], v[100:103], v[96:99], v[2:5]
	s_cbranch_scc0 .LBB0_379
	s_barrier
	s_nop 5
	ds_write_b128 v9, v[2:5]
	s_waitcnt lgkmcnt(0)
	s_barrier
	s_and_saveexec_b64 s[8:9], s[0:1]
	s_cbranch_execz .LBB0_377
	ds_read_b128 v[24:27], v13
	v_lshl_add_u64 v[28:29], s[6:7], 0, v[6:7]
	v_or_b32_e32 v15, v28, v8
	v_mad_u64_u32 v[30:31], s[6:7], v15, s51, v[10:11]
	s_waitcnt lgkmcnt(0)
	v_add_f32_e32 v2, v2, v24
	v_cvt_pk_bf16_f32 v2, v2, s0
	v_mad_i32_i24 v31, v29, s51, v31
	global_store_short v[30:31], v2, off
	v_add_f32_e32 v2, v3, v25
	v_cvt_pk_bf16_f32 v15, v2, s0
	v_or_b32_e32 v2, v28, v12
	v_mad_u64_u32 v[2:3], s[6:7], v2, s51, v[10:11]
	v_mad_i32_i24 v3, v29, s51, v3
	global_store_short v[2:3], v15, off
	v_add_f32_e32 v2, v4, v26
	v_cvt_pk_bf16_f32 v4, v2, s0
	v_or_b32_e32 v2, v28, v14
	v_mad_u64_u32 v[2:3], s[6:7], v2, s51, v[10:11]
	v_mad_i32_i24 v3, v29, s51, v3
	global_store_short v[2:3], v4, off
	v_add_f32_e32 v2, v5, v27
	v_cvt_pk_bf16_f32 v4, v2, s0
	v_or_b32_e32 v2, v28, v16
	v_mad_u64_u32 v[2:3], s[6:7], v2, s51, v[10:11]
	v_mad_i32_i24 v3, v29, s51, v3
	global_store_short v[2:3], v4, off
	s_branch .LBB0_377

; __device__ __forceinline__ float bf2f(u16 h) { return __uint_as_float(((unsigned)h) << 16); }
; __device__ void nvec_items(const Ctx& p, const int hd) {
;     ...
;   for (int item = blockIdx.x; item < 2 * 256; item += gridDim.x) {
;     const int b = item >> 8, d = (item & 255) * 8 + w;
;     const int bh = b * 4 + hd;
;     float st = 0.f;
;     for (int c = 0; c < 3; ++c) {
;       float s = 0.f;
;       for (int k = 0; k < 4; ++k) {
;         uint4 r = *(const uint4*)(KTh + ((long)b * 2048 + d) * SEQ + c * 2048 + k * 512 + lane * 8);
;         s += bf2f(r.x & 0xffff) + bf2f(r.x >> 16) + bf2f(r.y & 0xffff) + bf2f(r.y >> 16) +
;              bf2f(r.z & 0xffff) + bf2f(r.z >> 16) + bf2f(r.w & 0xffff) + bf2f(r.w >> 16);
;       }
;       s = wave_sum(s);
;       if (c > 0) st *= __expf(gA[bh * SEQ + c * 2048 - 1] - gA[bh * SEQ + c * 2048 + 2047]);
;       st += s;
;       if (lane == 0) nv[(b * 3 + c) * 2048 + d] = st;
.LBB0_591:
	s_ashr_i32 s6, s15, 8
	s_and_b32 s7, s14, 0x7f8
	v_add_u32_e32 v2, s7, v6
	s_ashr_i32 s7, s6, 31
	s_lshl_b64 s[8:9], s[6:7], 25
	v_ashrrev_i32_e32 v3, 31, v2
	s_add_u32 s8, s10, s8
	s_addc_u32 s9, s11, s9
	s_waitcnt lgkmcnt(0)
	v_lshlrev_b64 v[4:5], 14, v[2:3]
	v_lshl_add_u64 v[4:5], s[8:9], 0, v[4:5]
	v_lshl_add_u64 v[4:5], v[4:5], 0, v[0:1]
	global_load_dwordx4 v[40:43], v[4:5], off
	global_load_dwordx4 v[44:47], v[4:5], off offset:1024
	global_load_dwordx4 v[48:51], v[4:5], off offset:2048
	global_load_dwordx4 v[52:55], v[4:5], off offset:3072
	v_add_co_u32_e32 v88, vcc, 0x1000, v4
	s_nop 1
	v_addc_co_u32_e32 v89, vcc, 0, v5, vcc
	global_load_dwordx4 v[56:59], v[88:89], off
	global_load_dwordx4 v[60:63], v[88:89], off offset:1024
	global_load_dwordx4 v[64:67], v[88:89], off offset:2048
	global_load_dwordx4 v[68:71], v[88:89], off offset:3072
	v_add_co_u32_e32 v90, vcc, 0x2000, v4
	s_nop 1
	v_addc_co_u32_e32 v91, vcc, 0, v5, vcc
	global_load_dwordx4 v[72:75], v[90:91], off
	global_load_dwordx4 v[76:79], v[90:91], off offset:1024
	global_load_dwordx4 v[80:83], v[90:91], off offset:2048
	global_load_dwordx4 v[84:87], v[90:91], off offset:3072
	s_mul_i32 s16, s6, 0x1800
	s_waitcnt vmcnt(0) lgkmcnt(0)
	v_lshlrev_b32_e32 v3, 16, v40
	v_and_b32_e32 v13, 0xffff0000, v40
	v_add_f32_e32 v3, v3, v13
	v_lshlrev_b32_e32 v13, 16, v41
	v_add_f32_e32 v3, v3, v13
	v_and_b32_e32 v13, 0xffff0000, v41
	v_add_f32_e32 v3, v3, v13
	v_lshlrev_b32_e32 v13, 16, v42
	v_add_f32_e32 v3, v3, v13
	v_and_b32_e32 v13, 0xffff0000, v42
	v_add_f32_e32 v3, v3, v13
	v_lshlrev_b32_e32 v13, 16, v43
	v_add_f32_e32 v3, v3, v13
	v_and_b32_e32 v13, 0xffff0000, v43
	v_add_f32_e32 v3, v3, v13
	v_add_f32_e32 v3, 0, v3
	s_waitcnt vmcnt(0) lgkmcnt(0)
	v_lshlrev_b32_e32 v13, 16, v44
	v_and_b32_e32 v44, 0xffff0000, v44
	v_add_f32_e32 v13, v13, v44
	v_lshlrev_b32_e32 v44, 16, v45
	v_add_f32_e32 v13, v13, v44
	v_and_b32_e32 v44, 0xffff0000, v45
	v_add_f32_e32 v13, v13, v44
	v_lshlrev_b32_e32 v44, 16, v46
	v_add_f32_e32 v13, v13, v44
	v_and_b32_e32 v44, 0xffff0000, v46
	v_add_f32_e32 v13, v13, v44
	v_lshlrev_b32_e32 v44, 16, v47
	v_add_f32_e32 v13, v13, v44
	v_and_b32_e32 v44, 0xffff0000, v47
	v_add_f32_e32 v13, v13, v44
	v_add_f32_e32 v3, v3, v13
	s_waitcnt vmcnt(0) lgkmcnt(0)
	v_lshlrev_b32_e32 v13, 16, v48
	v_and_b32_e32 v48, 0xffff0000, v48
	v_add_f32_e32 v13, v13, v48
	v_lshlrev_b32_e32 v48, 16, v49
	v_add_f32_e32 v13, v13, v48
	v_and_b32_e32 v48, 0xffff0000, v49
	v_add_f32_e32 v13, v13, v48
	v_lshlrev_b32_e32 v48, 16, v50
	v_add_f32_e32 v13, v13, v48
	v_and_b32_e32 v48, 0xffff0000, v50
	v_add_f32_e32 v13, v13, v48
	v_lshlrev_b32_e32 v48, 16, v51
	v_add_f32_e32 v13, v13, v48
	v_and_b32_e32 v48, 0xffff0000, v51
	v_add_f32_e32 v13, v13, v48
	v_add_f32_e32 v3, v3, v13
	s_waitcnt vmcnt(0) lgkmcnt(0)
	v_lshlrev_b32_e32 v13, 16, v52
	v_and_b32_e32 v52, 0xffff0000, v52
	v_add_f32_e32 v13, v13, v52
	v_lshlrev_b32_e32 v52, 16, v53
	v_add_f32_e32 v13, v13, v52
	v_and_b32_e32 v52, 0xffff0000, v53
	v_add_f32_e32 v13, v13, v52
	v_lshlrev_b32_e32 v52, 16, v54
	v_add_f32_e32 v13, v13, v52
	v_and_b32_e32 v52, 0xffff0000, v54
	v_add_f32_e32 v13, v13, v52
	v_lshlrev_b32_e32 v52, 16, v55
	v_add_f32_e32 v13, v13, v52
	v_and_b32_e32 v52, 0xffff0000, v55
	v_add_f32_e32 v13, v13, v52
	v_add_f32_e32 v3, v3, v13
	ds_bpermute_b32 v13, v7, v3
	s_waitcnt lgkmcnt(0)
	v_add_f32_e32 v3, v3, v13
	ds_bpermute_b32 v13, v8, v3
	s_waitcnt lgkmcnt(0)
	v_add_f32_e32 v3, v3, v13
	ds_bpermute_b32 v13, v9, v3
	s_waitcnt lgkmcnt(0)
	v_add_f32_e32 v3, v3, v13
	ds_bpermute_b32 v13, v10, v3
	s_waitcnt lgkmcnt(0)
	v_add_f32_e32 v3, v3, v13
	ds_bpermute_b32 v13, v11, v3
	s_waitcnt lgkmcnt(0)
	v_add_f32_e32 v3, v3, v13
	ds_bpermute_b32 v13, v12, v3
	s_waitcnt lgkmcnt(0)
	v_add_f32_e32 v3, v3, v13
	v_add_f32_e32 v13, 0, v3
	s_and_saveexec_b64 s[8:9], s[4:5]
	s_cbranch_execz .LBB0_593
	v_add_u32_e32 v52, s16, v2
	v_ashrrev_i32_e32 v53, 31, v52
	v_lshl_add_u64 v[52:53], v[52:53], 2, s[0:1]
	global_store_dword v[52:53], v13, off
; __device__ __forceinline__ float bf2f(u16 h) { return __uint_as_float(((unsigned)h) << 16); }
; __device__ void nvec_items(const Ctx& p, const int hd) {
;     ...
;     for (int c = 0; c < 3; ++c) {
;       float s = 0.f;
;       for (int k = 0; k < 4; ++k) {
;         uint4 r = *(const uint4*)(KTh + ((long)b * 2048 + d) * SEQ + c * 2048 + k * 512 + lane * 8);
;         s += bf2f(r.x & 0xffff) + bf2f(r.x >> 16) + bf2f(r.y & 0xffff) + bf2f(r.y >> 16) +
;              bf2f(r.z & 0xffff) + bf2f(r.z >> 16) + bf2f(r.w & 0xffff) + bf2f(r.w >> 16);
;       }
;       s = wave_sum(s);
;       if (c > 0) st *= __expf(gA[bh * SEQ + c * 2048 - 1] - gA[bh * SEQ + c * 2048 + 2047]);
;       st += s;
;       if (lane == 0) nv[(b * 3 + c) * 2048 + d] = st;
;     }
.LBB0_593:
	s_or_b64 exec, exec, s[8:9]
	v_add_co_u32_e32 v18, vcc, 0x1000, v4
	s_lshl_b32 s6, s6, 15
	s_nop 0
	v_addc_co_u32_e32 v19, vcc, 0, v5, vcc
	s_add_i32 s6, s6, s20
	s_ashr_i32 s7, s6, 31
	s_lshl_b64 s[6:7], s[6:7], 2
	s_add_u32 s18, s12, s6
	s_addc_u32 s17, s13, s7
	s_add_u32 s6, s18, 0x3ffc
	s_addc_u32 s7, s17, 0
	s_waitcnt vmcnt(0) lgkmcnt(0)
	v_lshlrev_b32_e32 v3, 16, v56
	v_and_b32_e32 v56, 0xffff0000, v56
	v_add_f32_e32 v3, v3, v56
	v_lshlrev_b32_e32 v56, 16, v57
	v_add_f32_e32 v3, v3, v56
	v_and_b32_e32 v56, 0xffff0000, v57
	v_add_f32_e32 v3, v3, v56
	v_lshlrev_b32_e32 v56, 16, v58
	v_add_f32_e32 v3, v3, v56
	v_and_b32_e32 v56, 0xffff0000, v58
	v_add_f32_e32 v3, v3, v56
	v_lshlrev_b32_e32 v56, 16, v59
	v_add_f32_e32 v3, v3, v56
	v_and_b32_e32 v56, 0xffff0000, v59
	v_add_f32_e32 v3, v3, v56
	v_add_f32_e32 v3, 0, v3
	s_waitcnt vmcnt(0) lgkmcnt(0)
	v_lshlrev_b32_e32 v20, 16, v60
	v_and_b32_e32 v60, 0xffff0000, v60
	v_add_f32_e32 v60, v20, v60
	v_lshlrev_b32_e32 v20, 16, v61
	v_add_f32_e32 v60, v60, v20
	v_and_b32_e32 v61, 0xffff0000, v61
	v_add_f32_e32 v60, v60, v61
	v_lshlrev_b32_e32 v61, 16, v62
	v_add_f32_e32 v60, v60, v61
	v_and_b32_e32 v61, 0xffff0000, v62
	v_add_f32_e32 v60, v60, v61
	v_lshlrev_b32_e32 v61, 16, v63
	v_add_f32_e32 v60, v60, v61
	v_and_b32_e32 v61, 0xffff0000, v63
	v_add_f32_e32 v60, v60, v61
	v_add_f32_e32 v3, v3, v60
	s_waitcnt vmcnt(0) lgkmcnt(0)
	v_lshlrev_b32_e32 v20, 16, v64
	v_and_b32_e32 v64, 0xffff0000, v64
	v_add_f32_e32 v64, v20, v64
	v_lshlrev_b32_e32 v20, 16, v65
	v_add_f32_e32 v64, v64, v20
	v_and_b32_e32 v65, 0xffff0000, v65
	v_add_f32_e32 v64, v64, v65
	v_lshlrev_b32_e32 v65, 16, v66
	v_add_f32_e32 v64, v64, v65
	v_and_b32_e32 v65, 0xffff0000, v66
	v_add_f32_e32 v64, v64, v65
	v_lshlrev_b32_e32 v65, 16, v67
	v_add_f32_e32 v64, v64, v65
	v_and_b32_e32 v65, 0xffff0000, v67
	v_add_f32_e32 v64, v64, v65
	v_add_f32_e32 v3, v3, v64
	s_waitcnt vmcnt(0) lgkmcnt(0)
	v_lshlrev_b32_e32 v18, 16, v68
	v_and_b32_e32 v68, 0xffff0000, v68
	v_add_f32_e32 v68, v18, v68
	v_lshlrev_b32_e32 v18, 16, v69
	v_add_f32_e32 v68, v68, v18
	v_and_b32_e32 v69, 0xffff0000, v69
	v_add_f32_e32 v68, v68, v69
	v_lshlrev_b32_e32 v69, 16, v70
	v_add_f32_e32 v68, v68, v69
	v_and_b32_e32 v69, 0xffff0000, v70
	v_add_f32_e32 v68, v68, v69
	v_lshlrev_b32_e32 v69, 16, v71
	v_add_f32_e32 v68, v68, v69
	v_and_b32_e32 v69, 0xffff0000, v71
	v_add_f32_e32 v68, v68, v69
	v_add_f32_e32 v3, v3, v68
	ds_bpermute_b32 v68, v7, v3
	v_mov_b32_e32 v70, s18
	v_mov_b32_e32 v71, s17
	s_waitcnt lgkmcnt(0)
	v_add_f32_e32 v3, v3, v68
	ds_bpermute_b32 v68, v8, v3
	s_waitcnt lgkmcnt(0)
	v_add_f32_e32 v3, v3, v68
	ds_bpermute_b32 v68, v9, v3
	s_waitcnt lgkmcnt(0)
	v_add_f32_e32 v3, v3, v68
	ds_bpermute_b32 v68, v10, v3
	s_waitcnt lgkmcnt(0)
	v_add_f32_e32 v3, v3, v68
	ds_bpermute_b32 v68, v11, v3
	s_waitcnt lgkmcnt(0)
	v_add_f32_e32 v3, v3, v68
	ds_bpermute_b32 v68, v12, v3
	s_waitcnt lgkmcnt(0)
	v_add_f32_e32 v3, v3, v68
	v_add_co_u32_e32 v68, vcc, 0x1000, v70
	s_nop 1
	v_addc_co_u32_e32 v69, vcc, 0, v71, vcc
	global_load_dword v18, v[68:69], off offset:4092
	v_add_co_u32_e32 v68, vcc, 0x3000, v70
	s_nop 1
	v_addc_co_u32_e32 v69, vcc, 0, v71, vcc
	global_load_dword v68, v[68:69], off offset:4092
	s_waitcnt vmcnt(0) lgkmcnt(0)
	v_sub_f32_e32 v68, v18, v68
	v_mul_f32_e32 v68, 0x3fb8aa3b, v68
	v_exp_f32_e32 v68, v68
	s_nop 0
	v_fmac_f32_e32 v3, v13, v68
	s_and_saveexec_b64 s[8:9], s[4:5]
	s_cbranch_execz .LBB0_595
	s_add_i32 s19, s16, 0x800
	v_add_u32_e32 v68, s19, v2
	v_ashrrev_i32_e32 v69, 31, v68
	v_lshl_add_u64 v[68:69], v[68:69], 2, s[0:1]
	global_store_dword v[68:69], v3, off
.LBB0_595:
	s_or_b64 exec, exec, s[8:9]
	v_add_co_u32_e32 v4, vcc, 0x2000, v4
	s_nop 1
	v_addc_co_u32_e32 v5, vcc, 0, v5, vcc
	s_waitcnt vmcnt(0) lgkmcnt(0)
	v_lshlrev_b32_e32 v13, 16, v72
	v_and_b32_e32 v72, 0xffff0000, v72
	v_add_f32_e32 v13, v13, v72
	v_lshlrev_b32_e32 v72, 16, v73
	v_add_f32_e32 v13, v13, v72
	v_and_b32_e32 v72, 0xffff0000, v73
	v_add_f32_e32 v13, v13, v72
	v_lshlrev_b32_e32 v72, 16, v74
	v_add_f32_e32 v13, v13, v72
	v_and_b32_e32 v72, 0xffff0000, v74
	v_add_f32_e32 v13, v13, v72
	v_lshlrev_b32_e32 v72, 16, v75
	v_add_f32_e32 v13, v13, v72
	v_and_b32_e32 v72, 0xffff0000, v75
	v_add_f32_e32 v13, v13, v72
	v_add_f32_e32 v13, 0, v13
	s_waitcnt vmcnt(0) lgkmcnt(0)
	v_lshlrev_b32_e32 v18, 16, v76
	v_and_b32_e32 v76, 0xffff0000, v76
	v_add_f32_e32 v76, v18, v76
	v_lshlrev_b32_e32 v18, 16, v77
	v_add_f32_e32 v76, v76, v18
	v_and_b32_e32 v77, 0xffff0000, v77
	v_add_f32_e32 v76, v76, v77
	v_lshlrev_b32_e32 v77, 16, v78
	v_add_f32_e32 v76, v76, v77
	v_and_b32_e32 v77, 0xffff0000, v78
	v_add_f32_e32 v76, v76, v77
	v_lshlrev_b32_e32 v77, 16, v79
	v_add_f32_e32 v76, v76, v77
	v_and_b32_e32 v77, 0xffff0000, v79
	v_add_f32_e32 v76, v76, v77
	v_add_f32_e32 v13, v13, v76
	s_waitcnt vmcnt(0) lgkmcnt(0)
	v_lshlrev_b32_e32 v18, 16, v80
	v_and_b32_e32 v80, 0xffff0000, v80
	v_add_f32_e32 v80, v18, v80
	v_lshlrev_b32_e32 v18, 16, v81
	v_add_f32_e32 v80, v80, v18
	v_and_b32_e32 v81, 0xffff0000, v81
	v_add_f32_e32 v80, v80, v81
	v_lshlrev_b32_e32 v81, 16, v82
	v_add_f32_e32 v80, v80, v81
	v_and_b32_e32 v81, 0xffff0000, v82
	v_add_f32_e32 v80, v80, v81
	v_lshlrev_b32_e32 v81, 16, v83
	v_add_f32_e32 v80, v80, v81
	v_and_b32_e32 v81, 0xffff0000, v83
	v_add_f32_e32 v80, v80, v81
	v_add_f32_e32 v13, v13, v80
	s_waitcnt vmcnt(0) lgkmcnt(0)
	v_lshlrev_b32_e32 v4, 16, v84
	v_and_b32_e32 v5, 0xffff0000, v84
	v_add_f32_e32 v4, v4, v5
	v_lshlrev_b32_e32 v5, 16, v85
	v_add_f32_e32 v4, v4, v5
	v_and_b32_e32 v5, 0xffff0000, v85
	v_add_f32_e32 v4, v4, v5
	v_lshlrev_b32_e32 v5, 16, v86
	v_add_f32_e32 v4, v4, v5
	v_and_b32_e32 v5, 0xffff0000, v86
	v_add_f32_e32 v4, v4, v5
	v_lshlrev_b32_e32 v5, 16, v87
	v_add_f32_e32 v4, v4, v5
	v_and_b32_e32 v5, 0xffff0000, v87
	v_add_f32_e32 v4, v4, v5
	v_add_f32_e32 v4, v13, v4
	ds_bpermute_b32 v5, v7, v4
	s_waitcnt lgkmcnt(0)
	v_add_f32_e32 v4, v4, v5
	ds_bpermute_b32 v5, v8, v4
	s_waitcnt lgkmcnt(0)
	v_add_f32_e32 v4, v4, v5
	ds_bpermute_b32 v5, v9, v4
	s_waitcnt lgkmcnt(0)
	v_add_f32_e32 v4, v4, v5
	ds_bpermute_b32 v5, v10, v4
	s_waitcnt lgkmcnt(0)
	v_add_f32_e32 v4, v4, v5
	ds_bpermute_b32 v5, v11, v4
	s_waitcnt lgkmcnt(0)
	v_add_f32_e32 v4, v4, v5
	ds_bpermute_b32 v5, v12, v4
	s_and_saveexec_b64 s[8:9], s[4:5]
	s_cbranch_execz .LBB0_590
	s_waitcnt lgkmcnt(0)
	v_add_f32_e32 v13, v4, v5
	v_mov_b64_e32 v[4:5], s[6:7]
	global_load_dword v84, v[4:5], off
	v_mov_b32_e32 v4, s18
	v_add_co_u32_e32 v4, vcc, 0x5000, v4
	v_mov_b32_e32 v5, s17
	s_nop 0
	v_addc_co_u32_e32 v5, vcc, 0, v5, vcc
	global_load_dword v4, v[4:5], off offset:4092
	s_addk_i32 s16, 0x1000
	v_add_u32_e32 v2, s16, v2
	s_waitcnt vmcnt(0) lgkmcnt(0)
	v_sub_f32_e32 v4, v84, v4
	v_mul_f32_e32 v4, 0x3fb8aa3b, v4
	v_exp_f32_e32 v4, v4
	s_nop 0
	v_fmac_f32_e32 v13, v3, v4
	v_ashrrev_i32_e32 v3, 31, v2
	v_lshl_add_u64 v[2:3], v[2:3], 2, s[0:1]
	global_store_dword v[2:3], v13, off
	s_branch .LBB0_590
